# layer-0 mix: hyena-ctx items of blocks >= 256 spread one per block over blocks 320..511 (was two on blocks 384..447)
# speedup vs baseline: 1.0155x; 1.0103x over previous
.LBB0_17:
	s_and_b64 vcc, exec, s[84:85]
	v_writelane_b32 v253, s3, 14
	s_cbranch_vccz .LBB0_23
	s_mul_hi_u32 s0, s3, 0xaaaaaaab
	s_lshr_b32 s2, s0, 2
	s_mul_i32 s8, s2, s81
	s_add_i32 s8, s8, s88
	s_cmpk_lt_i32 s8, 0x100
	s_cselect_b64 s[0:1], -1, 0
	s_cmpk_gt_i32 s8, 0xff
	s_cbranch_scc1 .LBB0_105
	s_mul_i32 s9, s2, -6
	s_add_i32 s9, s9, s3
	s_add_i32 s9, s9, 3
	s_cmp_gt_u32 s9, 5
	s_cselect_b32 s4, 6, 0
	s_sub_i32 s9, s9, s4
	s_cmp_lt_i32 s9, 1
	s_cbranch_scc1 .LBB0_106
	s_cmp_eq_u32 s9, 1
	s_mov_b64 s[4:5], -1
	s_cbranch_scc0 .LBB0_22
	s_add_i32 s2, s8, 0xffffffc0
	s_cmp_lt_u32 s2, 0xc0
	v_readlane_b32 s4, v252, 46
	s_cselect_b64 s[2:3], -1, 0
	v_readlane_b32 s5, v252, 47
	s_and_b64 s[2:3], s[4:5], s[2:3]
	s_and_b64 s[2:3], s[2:3], exec
	s_cselect_b32 s3, 2, -1
	s_cselect_b32 s2, s8, 0
	s_mov_b64 s[4:5], 0

.LBB0_114:
	s_cmp_gt_i32 s8, -1
	v_readlane_b32 s6, v253, 8
	s_cselect_b64 s[2:3], -1, 0
	v_readlane_b32 s7, v253, 9
	s_or_b64 s[2:3], s[6:7], s[2:3]
	s_mov_b64 s[4:5], -1
	s_and_b64 vcc, exec, s[2:3]
	s_cbranch_vccz .LBB0_116
	s_and_b32 s2, s8, 0xffffffc0
	s_cmpk_eq_i32 s2, 0x7000
	v_readlane_b32 s4, v252, 46
	s_cselect_b64 s[2:3], -1, 0
	v_readlane_b32 s5, v252, 47
	s_and_b64 s[2:3], s[4:5], s[2:3]
	s_sub_i32 s4, s8, 64
	s_and_b64 s[2:3], s[2:3], exec
	s_cselect_b32 s3, 2, -1
	s_cselect_b32 s2, s4, 0
	s_mov_b64 s[4:5], 0
